# FFN-up epilogue: first batch of conv-weight loads issued before the exchange barrier instead of after it
# baseline (speedup 1.0000x reference)
;     __device__ __forceinline__ void operator()(const f32x4 (&acc)[2][2][4][2], const Unit& u, int wr, int wc, int fr_, int fq_) const {
;     ...
;         asm volatile("s_waitcnt lgkmcnt(0)" ::: "memory"); __builtin_amdgcn_s_barrier(); asm volatile("" ::: "memory");
;         const int chg = u.pn * 128 + cl;
; #pragma unroll
;         for (int n = 0; n < 2; ++n) {
;             f32x4 w0[2], w1[2], w2[2], bv[2];
; #pragma unroll
;             for (int bj = 0; bj < 2; ++bj) { const int wcol = bj * 2816 + chg + 4 * n; w0[bj] = *(const f32x4*)(cw + wcol); w1[bj] = *(const f32x4*)(cw + 5632 + wcol); w2[bj] = *(const f32x4*)(cw + 2 * 5632 + wcol); bv[bj] = *(const f32x4*)(cb + wcol); }
.LBB0_1820:
	s_or_b64 exec, exec, s[8:9]
	v_lshl_add_u32 v178, s14, 7, v160
	v_ashrrev_i32_e32 v179, 31, v178
	v_lshlrev_b64 v[128:129], 2, v[178:179]
	v_lshl_add_u64 v[180:181], s[22:23], 0, v[128:129]
	v_lshl_add_u64 v[130:131], s[28:29], 0, v[128:129]
	v_lshl_add_u64 v[132:133], s[30:31], 0, v[128:129]
	v_lshl_add_u64 v[182:183], s[24:25], 0, v[128:129]
	v_add_u32_e32 v128, 0xb00, v178
	v_ashrrev_i32_e32 v129, 31, v128
	v_lshlrev_b64 v[144:145], 2, v[128:129]
	v_lshl_add_u64 v[128:129], s[22:23], 0, v[144:145]
	global_load_dwordx4 v[152:155], v[180:181], off
	global_load_dwordx4 v[148:151], v[130:131], off
	global_load_dwordx4 v[140:143], v[132:133], off
	global_load_dwordx4 v[156:159], v[182:183], off
	v_lshl_add_u64 v[130:131], s[28:29], 0, v[144:145]
	global_load_dwordx4 v[136:139], v[128:129], off
	global_load_dwordx4 v[132:135], v[130:131], off
	v_lshl_add_u64 v[128:129], s[30:31], 0, v[144:145]
	v_lshl_add_u64 v[144:145], s[24:25], 0, v[144:145]
	global_load_dwordx4 v[128:131], v[128:129], off
	global_load_dwordx4 v[144:147], v[144:145], off
	s_waitcnt lgkmcnt(0)
	s_barrier
	v_add_u32_e32 v161, -1, v233
	v_lshl_add_u32 v162, v162, 4, v233
	v_and_b32_e32 v161, 15, v161
	v_add_u32_e32 v163, 1, v233
	v_and_b32_e32 v162, 48, v162
	v_and_b32_e32 v163, 15, v163
	v_or3_b32 v161, v162, v161, v211
	v_lshlrev_b32_e32 v215, 2, v161
	v_or3_b32 v161, v162, v163, v211
	v_cmp_eq_u32_e64 s[10:11], 0, v233
	v_lshlrev_b32_e32 v222, 2, v161
	v_lshl_add_u32 v231, v160, 2, s66
	v_cndmask_b32_e64 v160, v127, v123, s[10:11]
	v_cndmask_b32_e64 v161, v126, v122, s[10:11]
	v_cndmask_b32_e64 v162, v125, v121, s[10:11]
	v_cndmask_b32_e64 v163, v124, v120, s[10:11]
	v_mov_b32_dpp v234, v124 row_ror:1 row_mask:0xf bank_mask:0xf
	s_nop 0
	v_mov_b32_dpp v186, v163 row_ror:15 row_mask:0xf bank_mask:0xf
	v_mov_b32_dpp v236, v125 row_ror:1 row_mask:0xf bank_mask:0xf
	v_mov_b32_dpp v187, v162 row_ror:15 row_mask:0xf bank_mask:0xf
	v_mov_b32_dpp v235, v126 row_ror:1 row_mask:0xf bank_mask:0xf
	v_mov_b32_dpp v192, v161 row_ror:15 row_mask:0xf bank_mask:0xf
	v_mov_b32_dpp v237, v127 row_ror:1 row_mask:0xf bank_mask:0xf
	v_mov_b32_dpp v193, v160 row_ror:15 row_mask:0xf bank_mask:0xf
	v_cndmask_b32_e64 v161, 0, 1, s[16:17]
	v_mov_b32_e32 v160, 0
	v_cmp_ne_u32_e64 s[8:9], 1, v161
	s_andn2_b64 vcc, exec, s[16:17]
	v_mov_b32_e32 v164, 0
	v_mov_b32_e32 v165, 0
	v_mov_b32_e32 v166, 0
	v_mov_b32_e32 v167, 0
	s_cbranch_vccnz .LBB0_1822
	ds_read_b128 v[164:167], v231
